# GEMM load segments: the LDS-DMA pieces are issued at the head of the segment (one LDS read between each M0 write and its load), the remaining LDS reads after them
# baseline (speedup 1.0000x reference)
.LBB0_32:
	s_add_u32 s12, s10, 0x100
	s_addc_u32 s13, s11, 0
	s_cmpk_eq_i32 s42, 0x52
	s_cselect_b32 s17, s1, s13
	s_cselect_b32 s16, s0, s12
	s_cselect_b32 s15, s9, s41
	s_cselect_b32 s14, s8, s40
	s_add_i32 m0, s23, 0xc000
	ds_read_b128 v[130:133], v204
	global_load_lds_dwordx4 v180, s[10:11]
	s_add_i32 m0, s23, 0xe000
	ds_read_b128 v[134:137], v204 offset:1024
	global_load_lds_dwordx4 v182, s[10:11]
	ds_read_b128 v[138:141], v204 offset:2048
	ds_read_b128 v[142:145], v204 offset:3072
	ds_read_b128 v[146:149], v205
	ds_read_b128 v[150:153], v205 offset:1024
	ds_read_b128 v[154:157], v205 offset:2048
	ds_read_b128 v[158:161], v205 offset:3072
	ds_read_b128 v[162:165], v208
	ds_read_b128 v[166:169], v208 offset:1024
	ds_read_b128 v[170:173], v208 offset:2048
	ds_read_b128 v[184:187], v208 offset:3072
	ds_read_b128 v[188:191], v208 offset:4096
	ds_read_b128 v[192:195], v208 offset:5120
	ds_read_b128 v[196:199], v208 offset:6144
	ds_read_b128 v[200:203], v208 offset:7168
	s_waitcnt vmcnt(8) lgkmcnt(0)
	s_barrier
	v_mfma_f32_16x16x32_bf16 v[126:129], v[130:133], v[162:165], v[126:129]
	v_mfma_f32_16x16x32_bf16 v[94:97], v[138:141], v[162:165], v[94:97]
	v_mfma_f32_16x16x32_bf16 v[122:125], v[130:133], v[170:173], v[122:125]
	v_mfma_f32_16x16x32_bf16 v[90:93], v[138:141], v[170:173], v[90:93]
	v_mfma_f32_16x16x32_bf16 v[118:121], v[130:133], v[188:191], v[118:121]
	v_mfma_f32_16x16x32_bf16 v[86:89], v[138:141], v[188:191], v[86:89]
	v_mfma_f32_16x16x32_bf16 v[114:117], v[130:133], v[196:199], v[114:117]
	v_mfma_f32_16x16x32_bf16 v[82:85], v[138:141], v[196:199], v[82:85]
	v_mfma_f32_16x16x32_bf16 v[126:129], v[134:137], v[166:169], v[126:129]
	v_mfma_f32_16x16x32_bf16 v[94:97], v[142:145], v[166:169], v[94:97]
	v_mfma_f32_16x16x32_bf16 v[122:125], v[134:137], v[184:187], v[122:125]
	v_mfma_f32_16x16x32_bf16 v[90:93], v[142:145], v[184:187], v[90:93]
	v_mfma_f32_16x16x32_bf16 v[118:121], v[134:137], v[192:195], v[118:121]
	v_mfma_f32_16x16x32_bf16 v[86:89], v[142:145], v[192:195], v[86:89]
	v_mfma_f32_16x16x32_bf16 v[114:117], v[134:137], v[200:203], v[114:117]
	v_mfma_f32_16x16x32_bf16 v[82:85], v[142:145], v[200:203], v[82:85]
	v_mfma_f32_16x16x32_bf16 v[66:69], v[146:149], v[162:165], v[66:69]
	v_mfma_f32_16x16x32_bf16 v[42:45], v[154:157], v[162:165], v[42:45]
	v_mfma_f32_16x16x32_bf16 v[58:61], v[146:149], v[170:173], v[58:61]
	v_mfma_f32_16x16x32_bf16 v[30:33], v[154:157], v[170:173], v[30:33]
	v_mfma_f32_16x16x32_bf16 v[54:57], v[146:149], v[188:191], v[54:57]
	v_mfma_f32_16x16x32_bf16 v[22:25], v[154:157], v[188:191], v[22:25]
	v_mfma_f32_16x16x32_bf16 v[50:53], v[146:149], v[196:199], v[50:53]
	v_mfma_f32_16x16x32_bf16 v[18:21], v[154:157], v[196:199], v[18:21]
	v_mfma_f32_16x16x32_bf16 v[66:69], v[150:153], v[166:169], v[66:69]
	v_mfma_f32_16x16x32_bf16 v[42:45], v[158:161], v[166:169], v[42:45]
	v_mfma_f32_16x16x32_bf16 v[58:61], v[150:153], v[184:187], v[58:61]
	v_mfma_f32_16x16x32_bf16 v[30:33], v[158:161], v[184:187], v[30:33]
	v_mfma_f32_16x16x32_bf16 v[54:57], v[150:153], v[192:195], v[54:57]
	v_mfma_f32_16x16x32_bf16 v[22:25], v[158:161], v[192:195], v[22:25]
	v_mfma_f32_16x16x32_bf16 v[50:53], v[150:153], v[200:203], v[50:53]
	v_mfma_f32_16x16x32_bf16 v[18:21], v[158:161], v[200:203], v[18:21]
	s_barrier
	s_add_i32 m0, s22, 0x10000
	ds_read_b128 v[162:165], v208 offset:16384
	global_load_lds_dwordx4 v178, s[14:15]
	s_add_i32 m0, s22, 0x12000
	s_add_u32 s10, s14, 0x158000
	s_addc_u32 s11, s15, 0
	ds_read_b128 v[166:169], v208 offset:17408
	global_load_lds_dwordx4 v176, s[14:15]
	s_add_i32 m0, s22, 0x14000
	ds_read_b128 v[170:173], v208 offset:18432
	global_load_lds_dwordx4 v178, s[10:11]
	s_add_i32 m0, s22, 0x16000
	ds_read_b128 v[184:187], v208 offset:19456
	global_load_lds_dwordx4 v176, s[10:11]
	s_mov_b32 m0, s23
	ds_read_b128 v[188:191], v208 offset:20480
	global_load_lds_dwordx4 v178, s[16:17]
	s_mov_b32 m0, s24
	ds_read_b128 v[192:195], v208 offset:21504
	global_load_lds_dwordx4 v176, s[16:17]
	ds_read_b128 v[196:199], v208 offset:22528
	ds_read_b128 v[200:203], v208 offset:23552
	s_waitcnt vmcnt(8) lgkmcnt(0)
	s_barrier
	v_mfma_f32_16x16x32_bf16 v[110:113], v[130:133], v[162:165], v[110:113]
	v_mfma_f32_16x16x32_bf16 v[78:81], v[138:141], v[162:165], v[78:81]
	v_mfma_f32_16x16x32_bf16 v[106:109], v[130:133], v[170:173], v[106:109]
	v_mfma_f32_16x16x32_bf16 v[74:77], v[138:141], v[170:173], v[74:77]
	v_mfma_f32_16x16x32_bf16 v[102:105], v[130:133], v[188:191], v[102:105]
	v_mfma_f32_16x16x32_bf16 v[70:73], v[138:141], v[188:191], v[70:73]
	v_mfma_f32_16x16x32_bf16 v[98:101], v[130:133], v[196:199], v[98:101]
	v_mfma_f32_16x16x32_bf16 v[62:65], v[138:141], v[196:199], v[62:65]
	v_mfma_f32_16x16x32_bf16 v[110:113], v[134:137], v[166:169], v[110:113]
	v_mfma_f32_16x16x32_bf16 v[78:81], v[142:145], v[166:169], v[78:81]
	v_mfma_f32_16x16x32_bf16 v[106:109], v[134:137], v[184:187], v[106:109]
	v_mfma_f32_16x16x32_bf16 v[74:77], v[142:145], v[184:187], v[74:77]
	v_mfma_f32_16x16x32_bf16 v[102:105], v[134:137], v[192:195], v[102:105]
	v_mfma_f32_16x16x32_bf16 v[70:73], v[142:145], v[192:195], v[70:73]
	v_mfma_f32_16x16x32_bf16 v[98:101], v[134:137], v[200:203], v[98:101]
	v_mfma_f32_16x16x32_bf16 v[62:65], v[142:145], v[200:203], v[62:65]
	v_mfma_f32_16x16x32_bf16 v[46:49], v[146:149], v[162:165], v[46:49]
	v_mfma_f32_16x16x32_bf16 v[12:15], v[154:157], v[162:165], v[12:15]
	v_mfma_f32_16x16x32_bf16 v[38:41], v[146:149], v[170:173], v[38:41]
	v_mfma_f32_16x16x32_bf16 v[8:11], v[154:157], v[170:173], v[8:11]
	v_mfma_f32_16x16x32_bf16 v[34:37], v[146:149], v[188:191], v[34:37]
	v_mfma_f32_16x16x32_bf16 v[4:7], v[154:157], v[188:191], v[4:7]
	v_mfma_f32_16x16x32_bf16 v[26:29], v[146:149], v[196:199], v[26:29]
	v_mfma_f32_16x16x32_bf16 v[0:3], v[154:157], v[196:199], v[0:3]
	v_mfma_f32_16x16x32_bf16 v[46:49], v[150:153], v[166:169], v[46:49]
	v_mfma_f32_16x16x32_bf16 v[12:15], v[158:161], v[166:169], v[12:15]
	v_mfma_f32_16x16x32_bf16 v[38:41], v[150:153], v[184:187], v[38:41]
	v_mfma_f32_16x16x32_bf16 v[8:11], v[158:161], v[184:187], v[8:11]
	v_mfma_f32_16x16x32_bf16 v[34:37], v[150:153], v[192:195], v[34:37]
	v_mfma_f32_16x16x32_bf16 v[4:7], v[158:161], v[192:195], v[4:7]
	v_mfma_f32_16x16x32_bf16 v[26:29], v[150:153], v[200:203], v[26:29]
	v_mfma_f32_16x16x32_bf16 v[0:3], v[158:161], v[200:203], v[0:3]
	s_barrier
	s_add_u32 s100, s16, 0x158000
	s_addc_u32 s101, s17, 0
	s_mov_b32 m0, s25
	ds_read_b128 v[130:133], v210
	global_load_lds_dwordx4 v178, s[100:101]
	s_mov_b32 m0, s26
	ds_read_b128 v[134:137], v210 offset:1024
	global_load_lds_dwordx4 v176, s[100:101]
	ds_read_b128 v[138:141], v210 offset:2048
	ds_read_b128 v[142:145], v210 offset:3072
	ds_read_b128 v[146:149], v211
	ds_read_b128 v[150:153], v211 offset:1024
	ds_read_b128 v[154:157], v211 offset:2048
	ds_read_b128 v[158:161], v211 offset:3072
	ds_read_b128 v[162:165], v208 offset:32768
	ds_read_b128 v[166:169], v208 offset:33792
	ds_read_b128 v[170:173], v208 offset:34816
	ds_read_b128 v[184:187], v208 offset:35840
	ds_read_b128 v[188:191], v208 offset:36864
	ds_read_b128 v[192:195], v208 offset:37888
	ds_read_b128 v[196:199], v208 offset:38912
	ds_read_b128 v[200:203], v208 offset:39936
	s_waitcnt vmcnt(8) lgkmcnt(0)
	s_barrier
	v_mfma_f32_16x16x32_bf16 v[126:129], v[130:133], v[162:165], v[126:129]
	v_mfma_f32_16x16x32_bf16 v[94:97], v[138:141], v[162:165], v[94:97]
	v_mfma_f32_16x16x32_bf16 v[122:125], v[130:133], v[170:173], v[122:125]
	v_mfma_f32_16x16x32_bf16 v[90:93], v[138:141], v[170:173], v[90:93]
	v_mfma_f32_16x16x32_bf16 v[118:121], v[130:133], v[188:191], v[118:121]
	v_mfma_f32_16x16x32_bf16 v[86:89], v[138:141], v[188:191], v[86:89]
	v_mfma_f32_16x16x32_bf16 v[114:117], v[130:133], v[196:199], v[114:117]
	v_mfma_f32_16x16x32_bf16 v[82:85], v[138:141], v[196:199], v[82:85]
	v_mfma_f32_16x16x32_bf16 v[126:129], v[134:137], v[166:169], v[126:129]
	v_mfma_f32_16x16x32_bf16 v[94:97], v[142:145], v[166:169], v[94:97]
	v_mfma_f32_16x16x32_bf16 v[122:125], v[134:137], v[184:187], v[122:125]
	v_mfma_f32_16x16x32_bf16 v[90:93], v[142:145], v[184:187], v[90:93]
	v_mfma_f32_16x16x32_bf16 v[118:121], v[134:137], v[192:195], v[118:121]
	v_mfma_f32_16x16x32_bf16 v[86:89], v[142:145], v[192:195], v[86:89]
	v_mfma_f32_16x16x32_bf16 v[114:117], v[134:137], v[200:203], v[114:117]
	v_mfma_f32_16x16x32_bf16 v[82:85], v[142:145], v[200:203], v[82:85]
	v_mfma_f32_16x16x32_bf16 v[66:69], v[146:149], v[162:165], v[66:69]
	v_mfma_f32_16x16x32_bf16 v[42:45], v[154:157], v[162:165], v[42:45]
	v_mfma_f32_16x16x32_bf16 v[58:61], v[146:149], v[170:173], v[58:61]
	v_mfma_f32_16x16x32_bf16 v[30:33], v[154:157], v[170:173], v[30:33]
	v_mfma_f32_16x16x32_bf16 v[54:57], v[146:149], v[188:191], v[54:57]
	v_mfma_f32_16x16x32_bf16 v[22:25], v[154:157], v[188:191], v[22:25]
	v_mfma_f32_16x16x32_bf16 v[50:53], v[146:149], v[196:199], v[50:53]
	v_mfma_f32_16x16x32_bf16 v[18:21], v[154:157], v[196:199], v[18:21]
	v_mfma_f32_16x16x32_bf16 v[66:69], v[150:153], v[166:169], v[66:69]
	v_mfma_f32_16x16x32_bf16 v[42:45], v[158:161], v[166:169], v[42:45]
	v_mfma_f32_16x16x32_bf16 v[58:61], v[150:153], v[184:187], v[58:61]
	v_mfma_f32_16x16x32_bf16 v[30:33], v[158:161], v[184:187], v[30:33]
	v_mfma_f32_16x16x32_bf16 v[54:57], v[150:153], v[192:195], v[54:57]
	v_mfma_f32_16x16x32_bf16 v[22:25], v[158:161], v[192:195], v[22:25]
	v_mfma_f32_16x16x32_bf16 v[50:53], v[150:153], v[200:203], v[50:53]
	v_mfma_f32_16x16x32_bf16 v[18:21], v[158:161], v[200:203], v[18:21]
	s_barrier
	s_add_i32 m0, s22, 0x17f80
	ds_read_b128 v[162:165], v208 offset:49152
	global_load_lds_dwordx4 v178, s[14:15] offset:128
	s_add_i32 m0, s22, 0x19f80
	ds_read_b128 v[166:169], v208 offset:50176
	global_load_lds_dwordx4 v176, s[14:15] offset:128
	s_add_i32 m0, s22, 0x1bf80
	ds_read_b128 v[170:173], v208 offset:51200
	global_load_lds_dwordx4 v178, s[10:11] offset:128
	s_add_i32 m0, s22, 0x1df80
	ds_read_b128 v[184:187], v208 offset:52224
	global_load_lds_dwordx4 v176, s[10:11] offset:128
	s_add_i32 m0, s31, 0xffffff80
	ds_read_b128 v[188:191], v208 offset:53248
	global_load_lds_dwordx4 v178, s[16:17] offset:128
	s_add_i32 m0, s34, 0xffffff80
	ds_read_b128 v[192:195], v208 offset:54272
	global_load_lds_dwordx4 v176, s[16:17] offset:128
	ds_read_b128 v[196:199], v208 offset:55296
	ds_read_b128 v[200:203], v208 offset:56320
	s_waitcnt vmcnt(8) lgkmcnt(0)
	s_barrier
	v_mfma_f32_16x16x32_bf16 v[110:113], v[130:133], v[162:165], v[110:113]
	v_mfma_f32_16x16x32_bf16 v[78:81], v[138:141], v[162:165], v[78:81]
	v_mfma_f32_16x16x32_bf16 v[106:109], v[130:133], v[170:173], v[106:109]
	v_mfma_f32_16x16x32_bf16 v[74:77], v[138:141], v[170:173], v[74:77]
	v_mfma_f32_16x16x32_bf16 v[102:105], v[130:133], v[188:191], v[102:105]
	v_mfma_f32_16x16x32_bf16 v[70:73], v[138:141], v[188:191], v[70:73]
	v_mfma_f32_16x16x32_bf16 v[98:101], v[130:133], v[196:199], v[98:101]
	v_mfma_f32_16x16x32_bf16 v[62:65], v[138:141], v[196:199], v[62:65]
	v_mfma_f32_16x16x32_bf16 v[110:113], v[134:137], v[166:169], v[110:113]
	v_mfma_f32_16x16x32_bf16 v[78:81], v[142:145], v[166:169], v[78:81]
	v_mfma_f32_16x16x32_bf16 v[106:109], v[134:137], v[184:187], v[106:109]
	v_mfma_f32_16x16x32_bf16 v[74:77], v[142:145], v[184:187], v[74:77]
	v_mfma_f32_16x16x32_bf16 v[102:105], v[134:137], v[192:195], v[102:105]
	v_mfma_f32_16x16x32_bf16 v[70:73], v[142:145], v[192:195], v[70:73]
	v_mfma_f32_16x16x32_bf16 v[98:101], v[134:137], v[200:203], v[98:101]
	v_mfma_f32_16x16x32_bf16 v[62:65], v[142:145], v[200:203], v[62:65]
	v_mfma_f32_16x16x32_bf16 v[46:49], v[146:149], v[162:165], v[46:49]
	v_mfma_f32_16x16x32_bf16 v[12:15], v[154:157], v[162:165], v[12:15]
	v_mfma_f32_16x16x32_bf16 v[38:41], v[146:149], v[170:173], v[38:41]
	v_mfma_f32_16x16x32_bf16 v[8:11], v[154:157], v[170:173], v[8:11]
	v_mfma_f32_16x16x32_bf16 v[34:37], v[146:149], v[188:191], v[34:37]
	v_mfma_f32_16x16x32_bf16 v[4:7], v[154:157], v[188:191], v[4:7]
	v_mfma_f32_16x16x32_bf16 v[26:29], v[146:149], v[196:199], v[26:29]
	v_mfma_f32_16x16x32_bf16 v[0:3], v[154:157], v[196:199], v[0:3]
	v_mfma_f32_16x16x32_bf16 v[46:49], v[150:153], v[166:169], v[46:49]
	v_mfma_f32_16x16x32_bf16 v[12:15], v[158:161], v[166:169], v[12:15]
	v_mfma_f32_16x16x32_bf16 v[38:41], v[150:153], v[184:187], v[38:41]
	v_mfma_f32_16x16x32_bf16 v[8:11], v[158:161], v[184:187], v[8:11]
	v_mfma_f32_16x16x32_bf16 v[34:37], v[150:153], v[192:195], v[34:37]
	v_mfma_f32_16x16x32_bf16 v[4:7], v[158:161], v[192:195], v[4:7]
	v_mfma_f32_16x16x32_bf16 v[26:29], v[150:153], v[200:203], v[26:29]
	v_mfma_f32_16x16x32_bf16 v[0:3], v[158:161], v[200:203], v[0:3]
	s_barrier
	s_add_i32 s42, s42, 2
	s_add_u32 s40, s40, 0x100
	s_addc_u32 s41, s41, 0
	s_cmpk_gt_u32 s42, 0x53
	s_mov_b64 s[10:11], s[12:13]
	s_cbranch_scc0 .LBB0_32
	s_and_b64 vcc, exec, s[6:7]
	s_cbranch_vccz .LBB0_35
	s_barrier

.LBB0_68:
	s_add_u32 s8, s6, 0xfff80080
	s_addc_u32 s9, s7, -1
	s_cmp_eq_u32 s51, 28
	s_cselect_b32 s11, s21, s9
	s_cselect_b32 s10, s28, s8
	s_cselect_b32 s9, s19, s31
	s_cselect_b32 s8, s29, s30
	s_add_i32 m0, s41, 0xc000
	ds_read_b128 v[54:57], v214
	global_load_lds_dwordx4 v180, s[6:7]
	s_add_i32 m0, s41, 0xe000
	ds_read_b128 v[62:65], v214 offset:1024
	global_load_lds_dwordx4 v182, s[6:7]
	ds_read_b128 v[66:69], v214 offset:2048
	ds_read_b128 v[70:73], v214 offset:3072
	ds_read_b128 v[74:77], v215
	ds_read_b128 v[78:81], v215 offset:1024
	ds_read_b128 v[82:85], v215 offset:2048
	ds_read_b128 v[86:89], v215 offset:3072
	ds_read_b128 v[170:173], v192
	ds_read_b128 v[184:187], v192 offset:1024
	ds_read_b128 v[194:197], v192 offset:2048
	ds_read_b128 v[198:201], v192 offset:3072
	ds_read_b128 v[202:205], v192 offset:4096
	ds_read_b128 v[206:209], v192 offset:5120
	ds_read_b128 v[210:213], v192 offset:6144
	ds_read_b128 v[222:225], v192 offset:7168
	s_waitcnt vmcnt(8) lgkmcnt(0)
	s_barrier
	v_mfma_f32_16x16x32_bf16 v[150:153], v[54:57], v[170:173], v[150:153]
	v_mfma_f32_16x16x32_bf16 v[142:145], v[66:69], v[170:173], v[142:145]
	v_mfma_f32_16x16x32_bf16 v[134:137], v[54:57], v[194:197], v[134:137]
	v_mfma_f32_16x16x32_bf16 v[126:129], v[66:69], v[194:197], v[126:129]
	v_mfma_f32_16x16x32_bf16 v[118:121], v[54:57], v[202:205], v[118:121]
	v_mfma_f32_16x16x32_bf16 v[114:117], v[66:69], v[202:205], v[114:117]
	v_mfma_f32_16x16x32_bf16 v[110:113], v[54:57], v[210:213], v[110:113]
	v_mfma_f32_16x16x32_bf16 v[106:109], v[66:69], v[210:213], v[106:109]
	v_mfma_f32_16x16x32_bf16 v[150:153], v[62:65], v[184:187], v[150:153]
	v_mfma_f32_16x16x32_bf16 v[142:145], v[70:73], v[184:187], v[142:145]
	v_mfma_f32_16x16x32_bf16 v[134:137], v[62:65], v[198:201], v[134:137]
	v_mfma_f32_16x16x32_bf16 v[126:129], v[70:73], v[198:201], v[126:129]
	v_mfma_f32_16x16x32_bf16 v[118:121], v[62:65], v[206:209], v[118:121]
	v_mfma_f32_16x16x32_bf16 v[114:117], v[70:73], v[206:209], v[114:117]
	v_mfma_f32_16x16x32_bf16 v[110:113], v[62:65], v[222:225], v[110:113]
	v_mfma_f32_16x16x32_bf16 v[106:109], v[70:73], v[222:225], v[106:109]
	v_mfma_f32_16x16x32_bf16 v[158:161], v[74:77], v[170:173], v[158:161]
	v_mfma_f32_16x16x32_bf16 v[154:157], v[82:85], v[170:173], v[154:157]
	v_mfma_f32_16x16x32_bf16 v[146:149], v[74:77], v[194:197], v[146:149]
	v_mfma_f32_16x16x32_bf16 v[138:141], v[82:85], v[194:197], v[138:141]
	v_mfma_f32_16x16x32_bf16 v[130:133], v[74:77], v[202:205], v[130:133]
	v_mfma_f32_16x16x32_bf16 v[122:125], v[82:85], v[202:205], v[122:125]
	v_mfma_f32_16x16x32_bf16 v[102:105], v[74:77], v[210:213], v[102:105]
	v_mfma_f32_16x16x32_bf16 v[98:101], v[82:85], v[210:213], v[98:101]
	v_mfma_f32_16x16x32_bf16 v[158:161], v[78:81], v[184:187], v[158:161]
	v_mfma_f32_16x16x32_bf16 v[154:157], v[86:89], v[184:187], v[154:157]
	v_mfma_f32_16x16x32_bf16 v[146:149], v[78:81], v[198:201], v[146:149]
	v_mfma_f32_16x16x32_bf16 v[138:141], v[86:89], v[198:201], v[138:141]
	v_mfma_f32_16x16x32_bf16 v[130:133], v[78:81], v[206:209], v[130:133]
	v_mfma_f32_16x16x32_bf16 v[122:125], v[86:89], v[206:209], v[122:125]
	v_mfma_f32_16x16x32_bf16 v[102:105], v[78:81], v[222:225], v[102:105]
	v_mfma_f32_16x16x32_bf16 v[98:101], v[86:89], v[222:225], v[98:101]
	s_barrier
	s_add_i32 m0, s38, 0x10000
	ds_read_b128 v[170:173], v192 offset:16384
	global_load_lds_dwordx4 v166, s[8:9]
	s_add_i32 m0, s38, 0x12000
	s_add_u32 s52, s8, 0x80000
	s_addc_u32 s53, s9, 0
	ds_read_b128 v[184:187], v192 offset:17408
	global_load_lds_dwordx4 v162, s[8:9]
	s_add_i32 m0, s38, 0x14000
	ds_read_b128 v[194:197], v192 offset:18432
	global_load_lds_dwordx4 v166, s[52:53]
	s_add_i32 m0, s38, 0x16000
	ds_read_b128 v[198:201], v192 offset:19456
	global_load_lds_dwordx4 v162, s[52:53]
	s_mov_b32 m0, s41
	ds_read_b128 v[202:205], v192 offset:20480
	global_load_lds_dwordx4 v168, s[10:11]
	s_mov_b32 m0, s42
	ds_read_b128 v[206:209], v192 offset:21504
	global_load_lds_dwordx4 v164, s[10:11]
	ds_read_b128 v[210:213], v192 offset:22528
	ds_read_b128 v[222:225], v192 offset:23552
	s_waitcnt vmcnt(8) lgkmcnt(0)
	s_barrier
	v_mfma_f32_16x16x32_bf16 v[58:61], v[54:57], v[170:173], v[58:61]
	v_mfma_f32_16x16x32_bf16 v[46:49], v[66:69], v[170:173], v[46:49]
	v_mfma_f32_16x16x32_bf16 v[38:41], v[54:57], v[194:197], v[38:41]
	v_mfma_f32_16x16x32_bf16 v[30:33], v[66:69], v[194:197], v[30:33]
	v_mfma_f32_16x16x32_bf16 v[22:25], v[54:57], v[202:205], v[22:25]
	v_mfma_f32_16x16x32_bf16 v[18:21], v[66:69], v[202:205], v[18:21]
	v_mfma_f32_16x16x32_bf16 v[8:11], v[54:57], v[210:213], v[8:11]
	v_mfma_f32_16x16x32_bf16 v[12:15], v[66:69], v[210:213], v[12:15]
	v_mfma_f32_16x16x32_bf16 v[58:61], v[62:65], v[184:187], v[58:61]
	v_mfma_f32_16x16x32_bf16 v[46:49], v[70:73], v[184:187], v[46:49]
	v_mfma_f32_16x16x32_bf16 v[38:41], v[62:65], v[198:201], v[38:41]
	v_mfma_f32_16x16x32_bf16 v[30:33], v[70:73], v[198:201], v[30:33]
	v_mfma_f32_16x16x32_bf16 v[22:25], v[62:65], v[206:209], v[22:25]
	v_mfma_f32_16x16x32_bf16 v[18:21], v[70:73], v[206:209], v[18:21]
	v_mfma_f32_16x16x32_bf16 v[8:11], v[62:65], v[222:225], v[8:11]
	v_mfma_f32_16x16x32_bf16 v[12:15], v[70:73], v[222:225], v[12:15]
	v_mfma_f32_16x16x32_bf16 v[50:53], v[74:77], v[194:197], v[50:53]
	v_mfma_f32_16x16x32_bf16 v[42:45], v[82:85], v[194:197], v[42:45]
	v_mfma_f32_16x16x32_bf16 v[34:37], v[74:77], v[202:205], v[34:37]
	v_mfma_f32_16x16x32_bf16 v[26:29], v[82:85], v[202:205], v[26:29]
	v_mfma_f32_16x16x32_bf16 v[0:3], v[74:77], v[210:213], v[0:3]
	v_mfma_f32_16x16x32_bf16 v[4:7], v[82:85], v[210:213], v[4:7]
	v_mfma_f32_16x16x32_bf16 v[54:57], v[74:77], v[170:173], v[94:97]
	v_mfma_f32_16x16x32_bf16 v[62:65], v[82:85], v[170:173], v[90:93]
	v_mfma_f32_16x16x32_bf16 v[50:53], v[78:81], v[198:201], v[50:53]
	v_mfma_f32_16x16x32_bf16 v[42:45], v[86:89], v[198:201], v[42:45]
	v_mfma_f32_16x16x32_bf16 v[34:37], v[78:81], v[206:209], v[34:37]
	v_mfma_f32_16x16x32_bf16 v[26:29], v[86:89], v[206:209], v[26:29]
	v_mfma_f32_16x16x32_bf16 v[0:3], v[78:81], v[222:225], v[0:3]
	v_mfma_f32_16x16x32_bf16 v[4:7], v[86:89], v[222:225], v[4:7]
	v_mfma_f32_16x16x32_bf16 v[54:57], v[78:81], v[184:187], v[54:57]
	v_mfma_f32_16x16x32_bf16 v[62:65], v[86:89], v[184:187], v[62:65]
	s_barrier
	s_add_u32 s100, s10, 0x80000
	s_addc_u32 s101, s11, 0
	s_mov_b32 m0, s43
	ds_read_b128 v[66:69], v234
	global_load_lds_dwordx4 v168, s[100:101]
	s_mov_b32 m0, s44
	ds_read_b128 v[70:73], v234 offset:1024
	global_load_lds_dwordx4 v164, s[100:101]
	ds_read_b128 v[74:77], v234 offset:2048
	ds_read_b128 v[78:81], v234 offset:3072
	ds_read_b128 v[82:85], v235
	ds_read_b128 v[86:89], v235 offset:1024
	ds_read_b128 v[170:173], v235 offset:2048
	ds_read_b128 v[184:187], v235 offset:3072
	ds_read_b128 v[90:93], v192 offset:32768
	ds_read_b128 v[94:97], v192 offset:33792
	ds_read_b128 v[194:197], v192 offset:34816
	ds_read_b128 v[198:201], v192 offset:35840
	ds_read_b128 v[202:205], v192 offset:36864
	ds_read_b128 v[206:209], v192 offset:37888
	ds_read_b128 v[210:213], v192 offset:38912
	ds_read_b128 v[222:225], v192 offset:39936
	s_waitcnt vmcnt(8) lgkmcnt(0)
	s_barrier
	v_mfma_f32_16x16x32_bf16 v[150:153], v[66:69], v[90:93], v[150:153]
	v_mfma_f32_16x16x32_bf16 v[142:145], v[74:77], v[90:93], v[142:145]
	v_mfma_f32_16x16x32_bf16 v[134:137], v[66:69], v[194:197], v[134:137]
	v_mfma_f32_16x16x32_bf16 v[126:129], v[74:77], v[194:197], v[126:129]
	v_mfma_f32_16x16x32_bf16 v[118:121], v[66:69], v[202:205], v[118:121]
	v_mfma_f32_16x16x32_bf16 v[114:117], v[74:77], v[202:205], v[114:117]
	v_mfma_f32_16x16x32_bf16 v[110:113], v[66:69], v[210:213], v[110:113]
	v_mfma_f32_16x16x32_bf16 v[106:109], v[74:77], v[210:213], v[106:109]
	v_mfma_f32_16x16x32_bf16 v[150:153], v[70:73], v[94:97], v[150:153]
	v_mfma_f32_16x16x32_bf16 v[142:145], v[78:81], v[94:97], v[142:145]
	v_mfma_f32_16x16x32_bf16 v[134:137], v[70:73], v[198:201], v[134:137]
	v_mfma_f32_16x16x32_bf16 v[126:129], v[78:81], v[198:201], v[126:129]
	v_mfma_f32_16x16x32_bf16 v[118:121], v[70:73], v[206:209], v[118:121]
	v_mfma_f32_16x16x32_bf16 v[114:117], v[78:81], v[206:209], v[114:117]
	v_mfma_f32_16x16x32_bf16 v[110:113], v[70:73], v[222:225], v[110:113]
	v_mfma_f32_16x16x32_bf16 v[106:109], v[78:81], v[222:225], v[106:109]
	v_mfma_f32_16x16x32_bf16 v[158:161], v[82:85], v[90:93], v[158:161]
	v_mfma_f32_16x16x32_bf16 v[90:93], v[170:173], v[90:93], v[154:157]
	v_mfma_f32_16x16x32_bf16 v[154:157], v[184:187], v[94:97], v[90:93]
	v_mfma_f32_16x16x32_bf16 v[90:93], v[82:85], v[194:197], v[146:149]
	v_mfma_f32_16x16x32_bf16 v[146:149], v[86:89], v[198:201], v[90:93]
	v_mfma_f32_16x16x32_bf16 v[90:93], v[170:173], v[194:197], v[138:141]
	v_mfma_f32_16x16x32_bf16 v[138:141], v[184:187], v[198:201], v[90:93]
	v_mfma_f32_16x16x32_bf16 v[90:93], v[82:85], v[202:205], v[130:133]
	v_mfma_f32_16x16x32_bf16 v[130:133], v[86:89], v[206:209], v[90:93]
	v_mfma_f32_16x16x32_bf16 v[90:93], v[170:173], v[202:205], v[122:125]
	v_mfma_f32_16x16x32_bf16 v[122:125], v[184:187], v[206:209], v[90:93]
	v_mfma_f32_16x16x32_bf16 v[90:93], v[82:85], v[210:213], v[102:105]
	v_mfma_f32_16x16x32_bf16 v[102:105], v[86:89], v[222:225], v[90:93]
	v_mfma_f32_16x16x32_bf16 v[90:93], v[170:173], v[210:213], v[98:101]
	v_mfma_f32_16x16x32_bf16 v[158:161], v[86:89], v[94:97], v[158:161]
	v_mfma_f32_16x16x32_bf16 v[98:101], v[184:187], v[222:225], v[90:93]
	s_barrier
	s_add_i32 m0, s38, 0x17f80
	ds_read_b128 v[90:93], v192 offset:49152
	global_load_lds_dwordx4 v166, s[8:9] offset:128
	s_add_i32 m0, s38, 0x19f80
	ds_read_b128 v[194:197], v192 offset:50176
	global_load_lds_dwordx4 v162, s[8:9] offset:128
	s_add_i32 m0, s38, 0x1bf80
	ds_read_b128 v[198:201], v192 offset:51200
	global_load_lds_dwordx4 v166, s[52:53] offset:128
	s_add_i32 m0, s38, 0x1df80
	ds_read_b128 v[202:205], v192 offset:52224
	global_load_lds_dwordx4 v162, s[52:53] offset:128
	s_add_i32 m0, s46, 0xffffff80
	ds_read_b128 v[206:209], v192 offset:53248
	global_load_lds_dwordx4 v168, s[10:11] offset:128
	s_add_i32 m0, s47, 0xffffff80
	ds_read_b128 v[210:213], v192 offset:54272
	global_load_lds_dwordx4 v164, s[10:11] offset:128
	ds_read_b128 v[222:225], v192 offset:55296
	ds_read_b128 v[230:233], v192 offset:56320
	s_waitcnt vmcnt(8) lgkmcnt(0)
	s_barrier
	v_mfma_f32_16x16x32_bf16 v[58:61], v[66:69], v[90:93], v[58:61]
	v_mfma_f32_16x16x32_bf16 v[46:49], v[74:77], v[90:93], v[46:49]
	v_mfma_f32_16x16x32_bf16 v[38:41], v[66:69], v[198:201], v[38:41]
	v_mfma_f32_16x16x32_bf16 v[30:33], v[74:77], v[198:201], v[30:33]
	v_mfma_f32_16x16x32_bf16 v[22:25], v[66:69], v[206:209], v[22:25]
	v_mfma_f32_16x16x32_bf16 v[18:21], v[74:77], v[206:209], v[18:21]
	v_mfma_f32_16x16x32_bf16 v[8:11], v[66:69], v[222:225], v[8:11]
	v_mfma_f32_16x16x32_bf16 v[12:15], v[74:77], v[222:225], v[12:15]
	v_mfma_f32_16x16x32_bf16 v[58:61], v[70:73], v[194:197], v[58:61]
	v_mfma_f32_16x16x32_bf16 v[46:49], v[78:81], v[194:197], v[46:49]
	v_mfma_f32_16x16x32_bf16 v[38:41], v[70:73], v[202:205], v[38:41]
	v_mfma_f32_16x16x32_bf16 v[30:33], v[78:81], v[202:205], v[30:33]
	v_mfma_f32_16x16x32_bf16 v[22:25], v[70:73], v[210:213], v[22:25]
	v_mfma_f32_16x16x32_bf16 v[18:21], v[78:81], v[210:213], v[18:21]
	v_mfma_f32_16x16x32_bf16 v[8:11], v[70:73], v[230:233], v[8:11]
	v_mfma_f32_16x16x32_bf16 v[12:15], v[78:81], v[230:233], v[12:15]
	v_mfma_f32_16x16x32_bf16 v[54:57], v[82:85], v[90:93], v[54:57]
	v_mfma_f32_16x16x32_bf16 v[94:97], v[86:89], v[194:197], v[54:57]
	v_mfma_f32_16x16x32_bf16 v[54:57], v[170:173], v[90:93], v[62:65]
	v_mfma_f32_16x16x32_bf16 v[50:53], v[82:85], v[198:201], v[50:53]
	v_mfma_f32_16x16x32_bf16 v[42:45], v[170:173], v[198:201], v[42:45]
	v_mfma_f32_16x16x32_bf16 v[34:37], v[82:85], v[206:209], v[34:37]
	v_mfma_f32_16x16x32_bf16 v[26:29], v[170:173], v[206:209], v[26:29]
	v_mfma_f32_16x16x32_bf16 v[0:3], v[82:85], v[222:225], v[0:3]
	v_mfma_f32_16x16x32_bf16 v[4:7], v[170:173], v[222:225], v[4:7]
	v_mfma_f32_16x16x32_bf16 v[90:93], v[184:187], v[194:197], v[54:57]
	v_mfma_f32_16x16x32_bf16 v[50:53], v[86:89], v[202:205], v[50:53]
	v_mfma_f32_16x16x32_bf16 v[42:45], v[184:187], v[202:205], v[42:45]
	v_mfma_f32_16x16x32_bf16 v[34:37], v[86:89], v[210:213], v[34:37]
	v_mfma_f32_16x16x32_bf16 v[26:29], v[184:187], v[210:213], v[26:29]
	v_mfma_f32_16x16x32_bf16 v[0:3], v[86:89], v[230:233], v[0:3]
	v_mfma_f32_16x16x32_bf16 v[4:7], v[184:187], v[230:233], v[4:7]
	s_barrier
	s_add_i32 s51, s51, 2
	s_add_u32 s6, s6, 0x100
	s_addc_u32 s7, s7, 0
	s_add_u32 s30, s30, 0x100
	s_addc_u32 s31, s31, 0
	s_cmp_gt_u32 s51, 29
	s_cbranch_scc0 .LBB0_68
	s_and_b64 vcc, exec, s[16:17]
	s_cbranch_vccz .LBB0_71
	s_barrier

.LBB0_108:
	s_add_u32 s16, s14, 0xfff80080
	s_addc_u32 s17, s15, -1
	s_cmp_eq_u32 s44, 28
	s_cselect_b32 s19, s9, s17
	s_cselect_b32 s18, s40, s16
	s_cselect_b32 s17, s7, s43
	s_cselect_b32 s16, s41, s42
	s_add_i32 m0, s25, 0xc000
	ds_read_b128 v[130:133], v170
	global_load_lds_dwordx4 v180, s[14:15]
	s_add_i32 m0, s25, 0xe000
	ds_read_b128 v[134:137], v170 offset:1024
	global_load_lds_dwordx4 v182, s[14:15]
	ds_read_b128 v[138:141], v170 offset:2048
	ds_read_b128 v[142:145], v170 offset:3072
	ds_read_b128 v[146:149], v171
	ds_read_b128 v[150:153], v171 offset:1024
	ds_read_b128 v[154:157], v171 offset:2048
	ds_read_b128 v[158:161], v171 offset:3072
	ds_read_b128 v[162:165], v208
	ds_read_b128 v[166:169], v208 offset:1024
	ds_read_b128 v[184:187], v208 offset:2048
	ds_read_b128 v[188:191], v208 offset:3072
	ds_read_b128 v[192:195], v208 offset:4096
	ds_read_b128 v[196:199], v208 offset:5120
	ds_read_b128 v[200:203], v208 offset:6144
	ds_read_b128 v[210:213], v208 offset:7168
	s_waitcnt vmcnt(8) lgkmcnt(0)
	s_barrier
	v_mfma_f32_16x16x32_bf16 v[126:129], v[130:133], v[162:165], v[126:129]
	v_mfma_f32_16x16x32_bf16 v[94:97], v[138:141], v[162:165], v[94:97]
	v_mfma_f32_16x16x32_bf16 v[122:125], v[130:133], v[184:187], v[122:125]
	v_mfma_f32_16x16x32_bf16 v[90:93], v[138:141], v[184:187], v[90:93]
	v_mfma_f32_16x16x32_bf16 v[118:121], v[130:133], v[192:195], v[118:121]
	v_mfma_f32_16x16x32_bf16 v[86:89], v[138:141], v[192:195], v[86:89]
	v_mfma_f32_16x16x32_bf16 v[114:117], v[130:133], v[200:203], v[114:117]
	v_mfma_f32_16x16x32_bf16 v[82:85], v[138:141], v[200:203], v[82:85]
	v_mfma_f32_16x16x32_bf16 v[126:129], v[134:137], v[166:169], v[126:129]
	v_mfma_f32_16x16x32_bf16 v[94:97], v[142:145], v[166:169], v[94:97]
	v_mfma_f32_16x16x32_bf16 v[122:125], v[134:137], v[188:191], v[122:125]
	v_mfma_f32_16x16x32_bf16 v[90:93], v[142:145], v[188:191], v[90:93]
	v_mfma_f32_16x16x32_bf16 v[118:121], v[134:137], v[196:199], v[118:121]
	v_mfma_f32_16x16x32_bf16 v[86:89], v[142:145], v[196:199], v[86:89]
	v_mfma_f32_16x16x32_bf16 v[114:117], v[134:137], v[210:213], v[114:117]
	v_mfma_f32_16x16x32_bf16 v[82:85], v[142:145], v[210:213], v[82:85]
	v_mfma_f32_16x16x32_bf16 v[66:69], v[146:149], v[162:165], v[66:69]
	v_mfma_f32_16x16x32_bf16 v[42:45], v[154:157], v[162:165], v[42:45]
	v_mfma_f32_16x16x32_bf16 v[58:61], v[146:149], v[184:187], v[58:61]
	v_mfma_f32_16x16x32_bf16 v[30:33], v[154:157], v[184:187], v[30:33]
	v_mfma_f32_16x16x32_bf16 v[54:57], v[146:149], v[192:195], v[54:57]
	v_mfma_f32_16x16x32_bf16 v[22:25], v[154:157], v[192:195], v[22:25]
	v_mfma_f32_16x16x32_bf16 v[50:53], v[146:149], v[200:203], v[50:53]
	v_mfma_f32_16x16x32_bf16 v[18:21], v[154:157], v[200:203], v[18:21]
	v_mfma_f32_16x16x32_bf16 v[66:69], v[150:153], v[166:169], v[66:69]
	v_mfma_f32_16x16x32_bf16 v[42:45], v[158:161], v[166:169], v[42:45]
	v_mfma_f32_16x16x32_bf16 v[58:61], v[150:153], v[188:191], v[58:61]
	v_mfma_f32_16x16x32_bf16 v[30:33], v[158:161], v[188:191], v[30:33]
	v_mfma_f32_16x16x32_bf16 v[54:57], v[150:153], v[196:199], v[54:57]
	v_mfma_f32_16x16x32_bf16 v[22:25], v[158:161], v[196:199], v[22:25]
	v_mfma_f32_16x16x32_bf16 v[50:53], v[150:153], v[210:213], v[50:53]
	v_mfma_f32_16x16x32_bf16 v[18:21], v[158:161], v[210:213], v[18:21]
	s_barrier
	s_add_i32 m0, s24, 0x10000
	ds_read_b128 v[162:165], v208 offset:16384
	global_load_lds_dwordx4 v178, s[16:17]
	s_add_i32 m0, s24, 0x12000
	s_add_u32 s46, s16, 0x80000
	s_addc_u32 s47, s17, 0
	ds_read_b128 v[166:169], v208 offset:17408
	global_load_lds_dwordx4 v176, s[16:17]
	s_add_i32 m0, s24, 0x14000
	ds_read_b128 v[184:187], v208 offset:18432
	global_load_lds_dwordx4 v178, s[46:47]
	s_add_i32 m0, s24, 0x16000
	ds_read_b128 v[188:191], v208 offset:19456
	global_load_lds_dwordx4 v176, s[46:47]
	s_mov_b32 m0, s25
	ds_read_b128 v[192:195], v208 offset:20480
	global_load_lds_dwordx4 v178, s[18:19]
	s_mov_b32 m0, s26
	ds_read_b128 v[196:199], v208 offset:21504
	global_load_lds_dwordx4 v176, s[18:19]
	ds_read_b128 v[200:203], v208 offset:22528
	ds_read_b128 v[210:213], v208 offset:23552
	s_waitcnt vmcnt(8) lgkmcnt(0)
	s_barrier
	v_mfma_f32_16x16x32_bf16 v[110:113], v[130:133], v[162:165], v[110:113]
	v_mfma_f32_16x16x32_bf16 v[78:81], v[138:141], v[162:165], v[78:81]
	v_mfma_f32_16x16x32_bf16 v[106:109], v[130:133], v[184:187], v[106:109]
	v_mfma_f32_16x16x32_bf16 v[74:77], v[138:141], v[184:187], v[74:77]
	v_mfma_f32_16x16x32_bf16 v[102:105], v[130:133], v[192:195], v[102:105]
	v_mfma_f32_16x16x32_bf16 v[70:73], v[138:141], v[192:195], v[70:73]
	v_mfma_f32_16x16x32_bf16 v[98:101], v[130:133], v[200:203], v[98:101]
	v_mfma_f32_16x16x32_bf16 v[62:65], v[138:141], v[200:203], v[62:65]
	v_mfma_f32_16x16x32_bf16 v[110:113], v[134:137], v[166:169], v[110:113]
	v_mfma_f32_16x16x32_bf16 v[78:81], v[142:145], v[166:169], v[78:81]
	v_mfma_f32_16x16x32_bf16 v[106:109], v[134:137], v[188:191], v[106:109]
	v_mfma_f32_16x16x32_bf16 v[74:77], v[142:145], v[188:191], v[74:77]
	v_mfma_f32_16x16x32_bf16 v[102:105], v[134:137], v[196:199], v[102:105]
	v_mfma_f32_16x16x32_bf16 v[70:73], v[142:145], v[196:199], v[70:73]
	v_mfma_f32_16x16x32_bf16 v[98:101], v[134:137], v[210:213], v[98:101]
	v_mfma_f32_16x16x32_bf16 v[62:65], v[142:145], v[210:213], v[62:65]
	v_mfma_f32_16x16x32_bf16 v[46:49], v[146:149], v[162:165], v[46:49]
	v_mfma_f32_16x16x32_bf16 v[12:15], v[154:157], v[162:165], v[12:15]
	v_mfma_f32_16x16x32_bf16 v[38:41], v[146:149], v[184:187], v[38:41]
	v_mfma_f32_16x16x32_bf16 v[8:11], v[154:157], v[184:187], v[8:11]
	v_mfma_f32_16x16x32_bf16 v[34:37], v[146:149], v[192:195], v[34:37]
	v_mfma_f32_16x16x32_bf16 v[4:7], v[154:157], v[192:195], v[4:7]
	v_mfma_f32_16x16x32_bf16 v[26:29], v[146:149], v[200:203], v[26:29]
	v_mfma_f32_16x16x32_bf16 v[0:3], v[154:157], v[200:203], v[0:3]
	v_mfma_f32_16x16x32_bf16 v[46:49], v[150:153], v[166:169], v[46:49]
	v_mfma_f32_16x16x32_bf16 v[12:15], v[158:161], v[166:169], v[12:15]
	v_mfma_f32_16x16x32_bf16 v[38:41], v[150:153], v[188:191], v[38:41]
	v_mfma_f32_16x16x32_bf16 v[8:11], v[158:161], v[188:191], v[8:11]
	v_mfma_f32_16x16x32_bf16 v[34:37], v[150:153], v[196:199], v[34:37]
	v_mfma_f32_16x16x32_bf16 v[4:7], v[158:161], v[196:199], v[4:7]
	v_mfma_f32_16x16x32_bf16 v[26:29], v[150:153], v[210:213], v[26:29]
	v_mfma_f32_16x16x32_bf16 v[0:3], v[158:161], v[210:213], v[0:3]
	s_barrier
	s_add_u32 s100, s18, 0x80000
	s_addc_u32 s101, s19, 0
	s_mov_b32 m0, s27
	ds_read_b128 v[130:133], v172
	global_load_lds_dwordx4 v178, s[100:101]
	s_mov_b32 m0, s28
	ds_read_b128 v[134:137], v172 offset:1024
	global_load_lds_dwordx4 v176, s[100:101]
	ds_read_b128 v[138:141], v172 offset:2048
	ds_read_b128 v[142:145], v172 offset:3072
	ds_read_b128 v[146:149], v173
	ds_read_b128 v[150:153], v173 offset:1024
	ds_read_b128 v[154:157], v173 offset:2048
	ds_read_b128 v[158:161], v173 offset:3072
	ds_read_b128 v[162:165], v208 offset:32768
	ds_read_b128 v[166:169], v208 offset:33792
	ds_read_b128 v[184:187], v208 offset:34816
	ds_read_b128 v[188:191], v208 offset:35840
	ds_read_b128 v[192:195], v208 offset:36864
	ds_read_b128 v[196:199], v208 offset:37888
	ds_read_b128 v[200:203], v208 offset:38912
	ds_read_b128 v[210:213], v208 offset:39936
	s_waitcnt vmcnt(8) lgkmcnt(0)
	s_barrier
	v_mfma_f32_16x16x32_bf16 v[126:129], v[130:133], v[162:165], v[126:129]
	v_mfma_f32_16x16x32_bf16 v[94:97], v[138:141], v[162:165], v[94:97]
	v_mfma_f32_16x16x32_bf16 v[122:125], v[130:133], v[184:187], v[122:125]
	v_mfma_f32_16x16x32_bf16 v[90:93], v[138:141], v[184:187], v[90:93]
	v_mfma_f32_16x16x32_bf16 v[118:121], v[130:133], v[192:195], v[118:121]
	v_mfma_f32_16x16x32_bf16 v[86:89], v[138:141], v[192:195], v[86:89]
	v_mfma_f32_16x16x32_bf16 v[114:117], v[130:133], v[200:203], v[114:117]
	v_mfma_f32_16x16x32_bf16 v[82:85], v[138:141], v[200:203], v[82:85]
	v_mfma_f32_16x16x32_bf16 v[126:129], v[134:137], v[166:169], v[126:129]
	v_mfma_f32_16x16x32_bf16 v[94:97], v[142:145], v[166:169], v[94:97]
	v_mfma_f32_16x16x32_bf16 v[122:125], v[134:137], v[188:191], v[122:125]
	v_mfma_f32_16x16x32_bf16 v[90:93], v[142:145], v[188:191], v[90:93]
	v_mfma_f32_16x16x32_bf16 v[118:121], v[134:137], v[196:199], v[118:121]
	v_mfma_f32_16x16x32_bf16 v[86:89], v[142:145], v[196:199], v[86:89]
	v_mfma_f32_16x16x32_bf16 v[114:117], v[134:137], v[210:213], v[114:117]
	v_mfma_f32_16x16x32_bf16 v[82:85], v[142:145], v[210:213], v[82:85]
	v_mfma_f32_16x16x32_bf16 v[66:69], v[146:149], v[162:165], v[66:69]
	v_mfma_f32_16x16x32_bf16 v[42:45], v[154:157], v[162:165], v[42:45]
	v_mfma_f32_16x16x32_bf16 v[58:61], v[146:149], v[184:187], v[58:61]
	v_mfma_f32_16x16x32_bf16 v[30:33], v[154:157], v[184:187], v[30:33]
	v_mfma_f32_16x16x32_bf16 v[54:57], v[146:149], v[192:195], v[54:57]
	v_mfma_f32_16x16x32_bf16 v[22:25], v[154:157], v[192:195], v[22:25]
	v_mfma_f32_16x16x32_bf16 v[50:53], v[146:149], v[200:203], v[50:53]
	v_mfma_f32_16x16x32_bf16 v[18:21], v[154:157], v[200:203], v[18:21]
	v_mfma_f32_16x16x32_bf16 v[66:69], v[150:153], v[166:169], v[66:69]
	v_mfma_f32_16x16x32_bf16 v[42:45], v[158:161], v[166:169], v[42:45]
	v_mfma_f32_16x16x32_bf16 v[58:61], v[150:153], v[188:191], v[58:61]
	v_mfma_f32_16x16x32_bf16 v[30:33], v[158:161], v[188:191], v[30:33]
	v_mfma_f32_16x16x32_bf16 v[54:57], v[150:153], v[196:199], v[54:57]
	v_mfma_f32_16x16x32_bf16 v[22:25], v[158:161], v[196:199], v[22:25]
	v_mfma_f32_16x16x32_bf16 v[50:53], v[150:153], v[210:213], v[50:53]
	v_mfma_f32_16x16x32_bf16 v[18:21], v[158:161], v[210:213], v[18:21]
	s_barrier
	s_add_i32 m0, s24, 0x17f80
	ds_read_b128 v[162:165], v208 offset:49152
	global_load_lds_dwordx4 v178, s[16:17] offset:128
	s_add_i32 m0, s24, 0x19f80
	ds_read_b128 v[166:169], v208 offset:50176
	global_load_lds_dwordx4 v176, s[16:17] offset:128
	s_add_i32 m0, s24, 0x1bf80
	ds_read_b128 v[184:187], v208 offset:51200
	global_load_lds_dwordx4 v178, s[46:47] offset:128
	s_add_i32 m0, s24, 0x1df80
	ds_read_b128 v[188:191], v208 offset:52224
	global_load_lds_dwordx4 v176, s[46:47] offset:128
	s_add_i32 m0, s35, 0xffffff80
	ds_read_b128 v[192:195], v208 offset:53248
	global_load_lds_dwordx4 v178, s[18:19] offset:128
	s_add_i32 m0, s36, 0xffffff80
	ds_read_b128 v[196:199], v208 offset:54272
	global_load_lds_dwordx4 v176, s[18:19] offset:128
	ds_read_b128 v[200:203], v208 offset:55296
	ds_read_b128 v[210:213], v208 offset:56320
	s_waitcnt vmcnt(8) lgkmcnt(0)
	s_barrier
	v_mfma_f32_16x16x32_bf16 v[110:113], v[130:133], v[162:165], v[110:113]
	v_mfma_f32_16x16x32_bf16 v[78:81], v[138:141], v[162:165], v[78:81]
	v_mfma_f32_16x16x32_bf16 v[106:109], v[130:133], v[184:187], v[106:109]
	v_mfma_f32_16x16x32_bf16 v[74:77], v[138:141], v[184:187], v[74:77]
	v_mfma_f32_16x16x32_bf16 v[102:105], v[130:133], v[192:195], v[102:105]
	v_mfma_f32_16x16x32_bf16 v[70:73], v[138:141], v[192:195], v[70:73]
	v_mfma_f32_16x16x32_bf16 v[98:101], v[130:133], v[200:203], v[98:101]
	v_mfma_f32_16x16x32_bf16 v[62:65], v[138:141], v[200:203], v[62:65]
	v_mfma_f32_16x16x32_bf16 v[110:113], v[134:137], v[166:169], v[110:113]
	v_mfma_f32_16x16x32_bf16 v[78:81], v[142:145], v[166:169], v[78:81]
	v_mfma_f32_16x16x32_bf16 v[106:109], v[134:137], v[188:191], v[106:109]
	v_mfma_f32_16x16x32_bf16 v[74:77], v[142:145], v[188:191], v[74:77]
	v_mfma_f32_16x16x32_bf16 v[102:105], v[134:137], v[196:199], v[102:105]
	v_mfma_f32_16x16x32_bf16 v[70:73], v[142:145], v[196:199], v[70:73]
	v_mfma_f32_16x16x32_bf16 v[98:101], v[134:137], v[210:213], v[98:101]
	v_mfma_f32_16x16x32_bf16 v[62:65], v[142:145], v[210:213], v[62:65]
	v_mfma_f32_16x16x32_bf16 v[46:49], v[146:149], v[162:165], v[46:49]
	v_mfma_f32_16x16x32_bf16 v[12:15], v[154:157], v[162:165], v[12:15]
	v_mfma_f32_16x16x32_bf16 v[38:41], v[146:149], v[184:187], v[38:41]
	v_mfma_f32_16x16x32_bf16 v[8:11], v[154:157], v[184:187], v[8:11]
	v_mfma_f32_16x16x32_bf16 v[34:37], v[146:149], v[192:195], v[34:37]
	v_mfma_f32_16x16x32_bf16 v[4:7], v[154:157], v[192:195], v[4:7]
	v_mfma_f32_16x16x32_bf16 v[26:29], v[146:149], v[200:203], v[26:29]
	v_mfma_f32_16x16x32_bf16 v[0:3], v[154:157], v[200:203], v[0:3]
	v_mfma_f32_16x16x32_bf16 v[46:49], v[150:153], v[166:169], v[46:49]
	v_mfma_f32_16x16x32_bf16 v[12:15], v[158:161], v[166:169], v[12:15]
	v_mfma_f32_16x16x32_bf16 v[38:41], v[150:153], v[188:191], v[38:41]
	v_mfma_f32_16x16x32_bf16 v[8:11], v[158:161], v[188:191], v[8:11]
	v_mfma_f32_16x16x32_bf16 v[34:37], v[150:153], v[196:199], v[34:37]
	v_mfma_f32_16x16x32_bf16 v[4:7], v[158:161], v[196:199], v[4:7]
	v_mfma_f32_16x16x32_bf16 v[26:29], v[150:153], v[210:213], v[26:29]
	v_mfma_f32_16x16x32_bf16 v[0:3], v[158:161], v[210:213], v[0:3]
	s_barrier
	s_add_i32 s44, s44, 2
	s_add_u32 s14, s14, 0x100
	s_addc_u32 s15, s15, 0
	s_add_u32 s42, s42, 0x100
	s_addc_u32 s43, s43, 0
	s_cmp_gt_u32 s44, 29
	s_cbranch_scc0 .LBB0_108
	s_and_b64 vcc, exec, s[2:3]
	s_movk_i32 s44, 0x1000
	s_cbranch_vccz .LBB0_111
	s_barrier

.LBB0_552:
	s_add_u32 s8, s6, 0xfffe0080
	s_addc_u32 s9, s7, -1
	s_cmp_eq_u32 s46, 4
	s_cselect_b32 s25, s19, s9
	s_cselect_b32 s24, s42, s8
	s_cselect_b32 s9, s17, s45
	s_cselect_b32 s8, s43, s44
	s_add_i32 m0, s31, 0xc000
	ds_read_b128 v[58:61], v168
	global_load_lds_dwordx4 v164, s[6:7]
	s_add_i32 m0, s31, 0xe000
	ds_read_b128 v[70:73], v168 offset:1024
	global_load_lds_dwordx4 v166, s[6:7]
	ds_read_b128 v[74:77], v168 offset:2048
	ds_read_b128 v[86:89], v168 offset:3072
	ds_read_b128 v[122:125], v169
	ds_read_b128 v[126:129], v169 offset:1024
	ds_read_b128 v[154:157], v169 offset:2048
	ds_read_b128 v[176:179], v169 offset:3072
	ds_read_b128 v[186:189], v185
	ds_read_b128 v[190:193], v185 offset:1024
	ds_read_b128 v[194:197], v185 offset:2048
	ds_read_b128 v[198:201], v185 offset:3072
	ds_read_b128 v[202:205], v185 offset:4096
	ds_read_b128 v[206:209], v185 offset:5120
	ds_read_b128 v[210:213], v185 offset:6144
	ds_read_b128 v[230:233], v185 offset:7168
	s_waitcnt vmcnt(8) lgkmcnt(0)
	s_barrier
	v_mfma_f32_16x16x32_bf16 v[150:153], v[58:61], v[186:189], v[150:153]
	v_mfma_f32_16x16x32_bf16 v[146:149], v[74:77], v[186:189], v[146:149]
	v_mfma_f32_16x16x32_bf16 v[142:145], v[58:61], v[194:197], v[142:145]
	v_mfma_f32_16x16x32_bf16 v[138:141], v[74:77], v[194:197], v[138:141]
	v_mfma_f32_16x16x32_bf16 v[134:137], v[58:61], v[202:205], v[134:137]
	v_mfma_f32_16x16x32_bf16 v[130:133], v[74:77], v[202:205], v[130:133]
	v_mfma_f32_16x16x32_bf16 v[118:121], v[58:61], v[210:213], v[118:121]
	v_mfma_f32_16x16x32_bf16 v[114:117], v[74:77], v[210:213], v[114:117]
	v_mfma_f32_16x16x32_bf16 v[150:153], v[70:73], v[190:193], v[150:153]
	v_mfma_f32_16x16x32_bf16 v[146:149], v[86:89], v[190:193], v[146:149]
	v_mfma_f32_16x16x32_bf16 v[142:145], v[70:73], v[198:201], v[142:145]
	v_mfma_f32_16x16x32_bf16 v[138:141], v[86:89], v[198:201], v[138:141]
	v_mfma_f32_16x16x32_bf16 v[134:137], v[70:73], v[206:209], v[134:137]
	v_mfma_f32_16x16x32_bf16 v[130:133], v[86:89], v[206:209], v[130:133]
	v_mfma_f32_16x16x32_bf16 v[118:121], v[70:73], v[230:233], v[118:121]
	v_mfma_f32_16x16x32_bf16 v[114:117], v[86:89], v[230:233], v[114:117]
	v_mfma_f32_16x16x32_bf16 v[66:69], v[122:125], v[186:189], v[66:69]
	v_mfma_f32_16x16x32_bf16 v[62:65], v[154:157], v[186:189], v[62:65]
	v_mfma_f32_16x16x32_bf16 v[54:57], v[122:125], v[194:197], v[54:57]
	v_mfma_f32_16x16x32_bf16 v[50:53], v[154:157], v[194:197], v[50:53]
	v_mfma_f32_16x16x32_bf16 v[46:49], v[122:125], v[202:205], v[46:49]
	v_mfma_f32_16x16x32_bf16 v[42:45], v[154:157], v[202:205], v[42:45]
	v_mfma_f32_16x16x32_bf16 v[38:41], v[122:125], v[210:213], v[38:41]
	v_mfma_f32_16x16x32_bf16 v[34:37], v[154:157], v[210:213], v[34:37]
	v_mfma_f32_16x16x32_bf16 v[66:69], v[126:129], v[190:193], v[66:69]
	v_mfma_f32_16x16x32_bf16 v[62:65], v[176:179], v[190:193], v[62:65]
	v_mfma_f32_16x16x32_bf16 v[54:57], v[126:129], v[198:201], v[54:57]
	v_mfma_f32_16x16x32_bf16 v[50:53], v[176:179], v[198:201], v[50:53]
	v_mfma_f32_16x16x32_bf16 v[46:49], v[126:129], v[206:209], v[46:49]
	v_mfma_f32_16x16x32_bf16 v[42:45], v[176:179], v[206:209], v[42:45]
	v_mfma_f32_16x16x32_bf16 v[38:41], v[126:129], v[230:233], v[38:41]
	v_mfma_f32_16x16x32_bf16 v[34:37], v[176:179], v[230:233], v[34:37]
	s_barrier
	s_add_i32 m0, s30, 0x10000
	ds_read_b128 v[186:189], v185 offset:16384
	global_load_lds_dwordx4 v16, s[8:9]
	s_add_i32 m0, s30, 0x12000
	s_add_u32 s48, s8, 0x20000
	s_addc_u32 s49, s9, 0
	ds_read_b128 v[190:193], v185 offset:17408
	global_load_lds_dwordx4 v158, s[8:9]
	s_add_i32 m0, s30, 0x14000
	ds_read_b128 v[194:197], v185 offset:18432
	global_load_lds_dwordx4 v16, s[48:49]
	s_add_i32 m0, s30, 0x16000
	ds_read_b128 v[198:201], v185 offset:19456
	global_load_lds_dwordx4 v158, s[48:49]
	s_mov_b32 m0, s31
	ds_read_b128 v[202:205], v185 offset:20480
	global_load_lds_dwordx4 v162, s[24:25]
	s_mov_b32 m0, s34
	ds_read_b128 v[206:209], v185 offset:21504
	global_load_lds_dwordx4 v160, s[24:25]
	ds_read_b128 v[210:213], v185 offset:22528
	ds_read_b128 v[230:233], v185 offset:23552
	s_waitcnt vmcnt(8) lgkmcnt(0)
	s_barrier
	v_mfma_f32_16x16x32_bf16 v[110:113], v[58:61], v[186:189], v[110:113]
	v_mfma_f32_16x16x32_bf16 v[106:109], v[74:77], v[186:189], v[106:109]
	v_mfma_f32_16x16x32_bf16 v[102:105], v[58:61], v[194:197], v[102:105]
	v_mfma_f32_16x16x32_bf16 v[98:101], v[74:77], v[194:197], v[98:101]
	v_mfma_f32_16x16x32_bf16 v[94:97], v[58:61], v[202:205], v[94:97]
	v_mfma_f32_16x16x32_bf16 v[90:93], v[74:77], v[202:205], v[90:93]
	v_mfma_f32_16x16x32_bf16 v[58:61], v[58:61], v[210:213], v[82:85]
	v_mfma_f32_16x16x32_bf16 v[110:113], v[70:73], v[190:193], v[110:113]
	v_mfma_f32_16x16x32_bf16 v[106:109], v[86:89], v[190:193], v[106:109]
	v_mfma_f32_16x16x32_bf16 v[102:105], v[70:73], v[198:201], v[102:105]
	v_mfma_f32_16x16x32_bf16 v[98:101], v[86:89], v[198:201], v[98:101]
	v_mfma_f32_16x16x32_bf16 v[94:97], v[70:73], v[206:209], v[94:97]
	v_mfma_f32_16x16x32_bf16 v[90:93], v[86:89], v[206:209], v[90:93]
	v_mfma_f32_16x16x32_bf16 v[58:61], v[70:73], v[230:233], v[58:61]
	v_mfma_f32_16x16x32_bf16 v[70:73], v[74:77], v[210:213], v[78:81]
	v_mfma_f32_16x16x32_bf16 v[70:73], v[86:89], v[230:233], v[70:73]
	v_mfma_f32_16x16x32_bf16 v[30:33], v[122:125], v[186:189], v[30:33]
	v_mfma_f32_16x16x32_bf16 v[26:29], v[154:157], v[186:189], v[26:29]
	v_mfma_f32_16x16x32_bf16 v[22:25], v[122:125], v[194:197], v[22:25]
	v_mfma_f32_16x16x32_bf16 v[18:21], v[154:157], v[194:197], v[18:21]
	v_mfma_f32_16x16x32_bf16 v[12:15], v[122:125], v[202:205], v[12:15]
	v_mfma_f32_16x16x32_bf16 v[8:11], v[154:157], v[202:205], v[8:11]
	v_mfma_f32_16x16x32_bf16 v[4:7], v[122:125], v[210:213], v[4:7]
	v_mfma_f32_16x16x32_bf16 v[0:3], v[154:157], v[210:213], v[0:3]
	v_mfma_f32_16x16x32_bf16 v[30:33], v[126:129], v[190:193], v[30:33]
	v_mfma_f32_16x16x32_bf16 v[26:29], v[176:179], v[190:193], v[26:29]
	v_mfma_f32_16x16x32_bf16 v[22:25], v[126:129], v[198:201], v[22:25]
	v_mfma_f32_16x16x32_bf16 v[18:21], v[176:179], v[198:201], v[18:21]
	v_mfma_f32_16x16x32_bf16 v[12:15], v[126:129], v[206:209], v[12:15]
	v_mfma_f32_16x16x32_bf16 v[8:11], v[176:179], v[206:209], v[8:11]
	v_mfma_f32_16x16x32_bf16 v[4:7], v[126:129], v[230:233], v[4:7]
	v_mfma_f32_16x16x32_bf16 v[0:3], v[176:179], v[230:233], v[0:3]
	s_barrier
	s_add_u32 s100, s24, 0x20000
	s_addc_u32 s101, s25, 0
	s_mov_b32 m0, s35
	ds_read_b128 v[74:77], v170
	global_load_lds_dwordx4 v162, s[100:101]
	s_mov_b32 m0, s36
	ds_read_b128 v[78:81], v170 offset:1024
	global_load_lds_dwordx4 v160, s[100:101]
	ds_read_b128 v[86:89], v170 offset:2048
	ds_read_b128 v[122:125], v170 offset:3072
	ds_read_b128 v[126:129], v171
	ds_read_b128 v[154:157], v171 offset:1024
	ds_read_b128 v[176:179], v171 offset:2048
	ds_read_b128 v[186:189], v171 offset:3072
	ds_read_b128 v[82:85], v185 offset:32768
	ds_read_b128 v[190:193], v185 offset:33792
	ds_read_b128 v[194:197], v185 offset:34816
	ds_read_b128 v[198:201], v185 offset:35840
	ds_read_b128 v[202:205], v185 offset:36864
	ds_read_b128 v[206:209], v185 offset:37888
	ds_read_b128 v[210:213], v185 offset:38912
	ds_read_b128 v[230:233], v185 offset:39936
	s_waitcnt vmcnt(8) lgkmcnt(0)
	s_barrier
	v_mfma_f32_16x16x32_bf16 v[150:153], v[74:77], v[82:85], v[150:153]
	v_mfma_f32_16x16x32_bf16 v[146:149], v[86:89], v[82:85], v[146:149]
	v_mfma_f32_16x16x32_bf16 v[142:145], v[74:77], v[194:197], v[142:145]
	v_mfma_f32_16x16x32_bf16 v[138:141], v[86:89], v[194:197], v[138:141]
	v_mfma_f32_16x16x32_bf16 v[134:137], v[74:77], v[202:205], v[134:137]
	v_mfma_f32_16x16x32_bf16 v[130:133], v[86:89], v[202:205], v[130:133]
	v_mfma_f32_16x16x32_bf16 v[118:121], v[74:77], v[210:213], v[118:121]
	v_mfma_f32_16x16x32_bf16 v[114:117], v[86:89], v[210:213], v[114:117]
	v_mfma_f32_16x16x32_bf16 v[150:153], v[78:81], v[190:193], v[150:153]
	v_mfma_f32_16x16x32_bf16 v[146:149], v[122:125], v[190:193], v[146:149]
	v_mfma_f32_16x16x32_bf16 v[142:145], v[78:81], v[198:201], v[142:145]
	v_mfma_f32_16x16x32_bf16 v[138:141], v[122:125], v[198:201], v[138:141]
	v_mfma_f32_16x16x32_bf16 v[134:137], v[78:81], v[206:209], v[134:137]
	v_mfma_f32_16x16x32_bf16 v[130:133], v[122:125], v[206:209], v[130:133]
	v_mfma_f32_16x16x32_bf16 v[118:121], v[78:81], v[230:233], v[118:121]
	v_mfma_f32_16x16x32_bf16 v[114:117], v[122:125], v[230:233], v[114:117]
	v_mfma_f32_16x16x32_bf16 v[66:69], v[126:129], v[82:85], v[66:69]
	v_mfma_f32_16x16x32_bf16 v[62:65], v[176:179], v[82:85], v[62:65]
	v_mfma_f32_16x16x32_bf16 v[54:57], v[126:129], v[194:197], v[54:57]
	v_mfma_f32_16x16x32_bf16 v[50:53], v[176:179], v[194:197], v[50:53]
	v_mfma_f32_16x16x32_bf16 v[46:49], v[126:129], v[202:205], v[46:49]
	v_mfma_f32_16x16x32_bf16 v[42:45], v[176:179], v[202:205], v[42:45]
	v_mfma_f32_16x16x32_bf16 v[38:41], v[126:129], v[210:213], v[38:41]
	v_mfma_f32_16x16x32_bf16 v[34:37], v[176:179], v[210:213], v[34:37]
	v_mfma_f32_16x16x32_bf16 v[66:69], v[154:157], v[190:193], v[66:69]
	v_mfma_f32_16x16x32_bf16 v[62:65], v[186:189], v[190:193], v[62:65]
	v_mfma_f32_16x16x32_bf16 v[54:57], v[154:157], v[198:201], v[54:57]
	v_mfma_f32_16x16x32_bf16 v[50:53], v[186:189], v[198:201], v[50:53]
	v_mfma_f32_16x16x32_bf16 v[46:49], v[154:157], v[206:209], v[46:49]
	v_mfma_f32_16x16x32_bf16 v[42:45], v[186:189], v[206:209], v[42:45]
	v_mfma_f32_16x16x32_bf16 v[38:41], v[154:157], v[230:233], v[38:41]
	v_mfma_f32_16x16x32_bf16 v[34:37], v[186:189], v[230:233], v[34:37]
	s_barrier
	s_add_i32 m0, s30, 0x17f80
	ds_read_b128 v[190:193], v185 offset:49152
	global_load_lds_dwordx4 v16, s[8:9] offset:128
	s_add_i32 m0, s30, 0x19f80
	ds_read_b128 v[194:197], v185 offset:50176
	global_load_lds_dwordx4 v158, s[8:9] offset:128
	s_add_i32 m0, s30, 0x1bf80
	ds_read_b128 v[198:201], v185 offset:51200
	global_load_lds_dwordx4 v16, s[48:49] offset:128
	s_add_i32 m0, s30, 0x1df80
	ds_read_b128 v[202:205], v185 offset:52224
	global_load_lds_dwordx4 v158, s[48:49] offset:128
	s_add_i32 m0, s38, 0xffffff80
	ds_read_b128 v[206:209], v185 offset:53248
	global_load_lds_dwordx4 v162, s[24:25] offset:128
	s_add_i32 m0, s39, 0xffffff80
	ds_read_b128 v[210:213], v185 offset:54272
	global_load_lds_dwordx4 v160, s[24:25] offset:128
	ds_read_b128 v[230:233], v185 offset:55296
	ds_read_b128 v[234:237], v185 offset:56320
	s_waitcnt vmcnt(8) lgkmcnt(0)
	s_barrier
	v_mfma_f32_16x16x32_bf16 v[82:85], v[74:77], v[190:193], v[110:113]
	v_mfma_f32_16x16x32_bf16 v[110:113], v[78:81], v[194:197], v[82:85]
	v_mfma_f32_16x16x32_bf16 v[82:85], v[86:89], v[190:193], v[106:109]
	v_mfma_f32_16x16x32_bf16 v[106:109], v[122:125], v[194:197], v[82:85]
	v_mfma_f32_16x16x32_bf16 v[82:85], v[74:77], v[198:201], v[102:105]
	v_mfma_f32_16x16x32_bf16 v[102:105], v[78:81], v[202:205], v[82:85]
	v_mfma_f32_16x16x32_bf16 v[82:85], v[86:89], v[198:201], v[98:101]
	v_mfma_f32_16x16x32_bf16 v[98:101], v[122:125], v[202:205], v[82:85]
	v_mfma_f32_16x16x32_bf16 v[82:85], v[74:77], v[206:209], v[94:97]
	v_mfma_f32_16x16x32_bf16 v[94:97], v[78:81], v[210:213], v[82:85]
	v_mfma_f32_16x16x32_bf16 v[82:85], v[86:89], v[206:209], v[90:93]
	v_mfma_f32_16x16x32_bf16 v[58:61], v[74:77], v[230:233], v[58:61]
	v_mfma_f32_16x16x32_bf16 v[90:93], v[122:125], v[210:213], v[82:85]
	v_mfma_f32_16x16x32_bf16 v[82:85], v[78:81], v[234:237], v[58:61]
	v_mfma_f32_16x16x32_bf16 v[58:61], v[86:89], v[230:233], v[70:73]
	v_mfma_f32_16x16x32_bf16 v[78:81], v[122:125], v[234:237], v[58:61]
	v_mfma_f32_16x16x32_bf16 v[30:33], v[126:129], v[190:193], v[30:33]
	v_mfma_f32_16x16x32_bf16 v[26:29], v[176:179], v[190:193], v[26:29]
	v_mfma_f32_16x16x32_bf16 v[22:25], v[126:129], v[198:201], v[22:25]
	v_mfma_f32_16x16x32_bf16 v[18:21], v[176:179], v[198:201], v[18:21]
	v_mfma_f32_16x16x32_bf16 v[12:15], v[126:129], v[206:209], v[12:15]
	v_mfma_f32_16x16x32_bf16 v[8:11], v[176:179], v[206:209], v[8:11]
	v_mfma_f32_16x16x32_bf16 v[4:7], v[126:129], v[230:233], v[4:7]
	v_mfma_f32_16x16x32_bf16 v[0:3], v[176:179], v[230:233], v[0:3]
	v_mfma_f32_16x16x32_bf16 v[30:33], v[154:157], v[194:197], v[30:33]
	v_mfma_f32_16x16x32_bf16 v[26:29], v[186:189], v[194:197], v[26:29]
	v_mfma_f32_16x16x32_bf16 v[22:25], v[154:157], v[202:205], v[22:25]
	v_mfma_f32_16x16x32_bf16 v[18:21], v[186:189], v[202:205], v[18:21]
	v_mfma_f32_16x16x32_bf16 v[12:15], v[154:157], v[210:213], v[12:15]
	v_mfma_f32_16x16x32_bf16 v[8:11], v[186:189], v[210:213], v[8:11]
	v_mfma_f32_16x16x32_bf16 v[4:7], v[154:157], v[234:237], v[4:7]
	v_mfma_f32_16x16x32_bf16 v[0:3], v[186:189], v[234:237], v[0:3]
	s_barrier
	s_add_i32 s46, s46, 2
	s_add_u32 s6, s6, 0x100
	s_addc_u32 s7, s7, 0
	s_add_u32 s44, s44, 0x100
	s_addc_u32 s45, s45, 0
	s_cmp_gt_u32 s46, 5
	s_cbranch_scc0 .LBB0_552
	s_and_b64 vcc, exec, s[14:15]
	s_cbranch_vccz .LBB0_555
	s_barrier

.LBB0_1018:
	s_add_u32 s26, s24, 0xfff80080
	s_addc_u32 s27, s25, -1
	s_cmp_eq_u32 s62, 28
	s_cselect_b32 s29, s19, s27
	s_cselect_b32 s28, s31, s26
	s_cselect_b32 s27, s17, s61
	s_cselect_b32 s26, s55, s60
	s_add_i32 m0, s39, 0xc000
	ds_read_b128 v[144:147], v168
	global_load_lds_dwordx4 v140, s[24:25]
	s_add_i32 m0, s39, 0xe000
	ds_read_b128 v[148:151], v168 offset:1024
	global_load_lds_dwordx4 v142, s[24:25]
	ds_read_b128 v[152:155], v168 offset:2048
	ds_read_b128 v[156:159], v168 offset:3072
	ds_read_b128 v[160:163], v169
	ds_read_b128 v[176:179], v169 offset:1024
	ds_read_b128 v[180:183], v169 offset:2048
	ds_read_b128 v[184:187], v169 offset:3072
	ds_read_b128 v[188:191], v167
	ds_read_b128 v[192:195], v167 offset:1024
	ds_read_b128 v[196:199], v167 offset:2048
	ds_read_b128 v[200:203], v167 offset:3072
	ds_read_b128 v[204:207], v167 offset:4096
	ds_read_b128 v[208:211], v167 offset:5120
	ds_read_b128 v[212:215], v167 offset:6144
	ds_read_b128 v[230:233], v167 offset:7168
	s_waitcnt vmcnt(8) lgkmcnt(0)
	s_barrier
	v_mfma_f32_16x16x32_bf16 v[66:69], v[144:147], v[188:191], v[66:69]
	v_mfma_f32_16x16x32_bf16 v[62:65], v[152:155], v[188:191], v[62:65]
	v_mfma_f32_16x16x32_bf16 v[58:61], v[144:147], v[196:199], v[58:61]
	v_mfma_f32_16x16x32_bf16 v[54:57], v[152:155], v[196:199], v[54:57]
	v_mfma_f32_16x16x32_bf16 v[46:49], v[144:147], v[204:207], v[46:49]
	v_mfma_f32_16x16x32_bf16 v[42:45], v[152:155], v[204:207], v[42:45]
	v_mfma_f32_16x16x32_bf16 v[38:41], v[144:147], v[212:215], v[38:41]
	v_mfma_f32_16x16x32_bf16 v[34:37], v[152:155], v[212:215], v[34:37]
	v_mfma_f32_16x16x32_bf16 v[66:69], v[148:151], v[192:195], v[66:69]
	v_mfma_f32_16x16x32_bf16 v[62:65], v[156:159], v[192:195], v[62:65]
	v_mfma_f32_16x16x32_bf16 v[58:61], v[148:151], v[200:203], v[58:61]
	v_mfma_f32_16x16x32_bf16 v[54:57], v[156:159], v[200:203], v[54:57]
	v_mfma_f32_16x16x32_bf16 v[46:49], v[148:151], v[208:211], v[46:49]
	v_mfma_f32_16x16x32_bf16 v[42:45], v[156:159], v[208:211], v[42:45]
	v_mfma_f32_16x16x32_bf16 v[38:41], v[148:151], v[230:233], v[38:41]
	v_mfma_f32_16x16x32_bf16 v[34:37], v[156:159], v[230:233], v[34:37]
	v_mfma_f32_16x16x32_bf16 v[126:129], v[160:163], v[188:191], v[126:129]
	v_mfma_f32_16x16x32_bf16 v[122:125], v[180:183], v[188:191], v[122:125]
	v_mfma_f32_16x16x32_bf16 v[118:121], v[160:163], v[196:199], v[118:121]
	v_mfma_f32_16x16x32_bf16 v[114:117], v[180:183], v[196:199], v[114:117]
	v_mfma_f32_16x16x32_bf16 v[110:113], v[160:163], v[204:207], v[110:113]
	v_mfma_f32_16x16x32_bf16 v[106:109], v[180:183], v[204:207], v[106:109]
	v_mfma_f32_16x16x32_bf16 v[102:105], v[160:163], v[212:215], v[102:105]
	v_mfma_f32_16x16x32_bf16 v[98:101], v[180:183], v[212:215], v[98:101]
	v_mfma_f32_16x16x32_bf16 v[126:129], v[176:179], v[192:195], v[126:129]
	v_mfma_f32_16x16x32_bf16 v[122:125], v[184:187], v[192:195], v[122:125]
	v_mfma_f32_16x16x32_bf16 v[118:121], v[176:179], v[200:203], v[118:121]
	v_mfma_f32_16x16x32_bf16 v[114:117], v[184:187], v[200:203], v[114:117]
	v_mfma_f32_16x16x32_bf16 v[110:113], v[176:179], v[208:211], v[110:113]
	v_mfma_f32_16x16x32_bf16 v[106:109], v[184:187], v[208:211], v[106:109]
	v_mfma_f32_16x16x32_bf16 v[102:105], v[176:179], v[230:233], v[102:105]
	v_mfma_f32_16x16x32_bf16 v[98:101], v[184:187], v[230:233], v[98:101]
	s_barrier
	s_add_i32 m0, s38, 0x10000
	ds_read_b128 v[188:191], v167 offset:16384
	global_load_lds_dwordx4 v132, s[26:27]
	s_add_i32 m0, s38, 0x12000
	s_add_u32 s64, s26, 0x80000
	s_addc_u32 s65, s27, 0
	ds_read_b128 v[192:195], v167 offset:17408
	global_load_lds_dwordx4 v136, s[26:27]
	s_add_i32 m0, s38, 0x14000
	ds_read_b128 v[196:199], v167 offset:18432
	global_load_lds_dwordx4 v132, s[64:65]
	s_add_i32 m0, s38, 0x16000
	ds_read_b128 v[200:203], v167 offset:19456
	global_load_lds_dwordx4 v136, s[64:65]
	s_mov_b32 m0, s39
	ds_read_b128 v[204:207], v167 offset:20480
	global_load_lds_dwordx4 v130, s[28:29]
	s_mov_b32 m0, s40
	ds_read_b128 v[208:211], v167 offset:21504
	global_load_lds_dwordx4 v134, s[28:29]
	ds_read_b128 v[212:215], v167 offset:22528
	ds_read_b128 v[230:233], v167 offset:23552
	s_waitcnt vmcnt(8) lgkmcnt(0)
	s_barrier
	v_mfma_f32_16x16x32_bf16 v[30:33], v[144:147], v[188:191], v[30:33]
	v_mfma_f32_16x16x32_bf16 v[26:29], v[152:155], v[188:191], v[26:29]
	v_mfma_f32_16x16x32_bf16 v[22:25], v[144:147], v[196:199], v[22:25]
	v_mfma_f32_16x16x32_bf16 v[18:21], v[152:155], v[196:199], v[18:21]
	v_mfma_f32_16x16x32_bf16 v[12:15], v[144:147], v[204:207], v[12:15]
	v_mfma_f32_16x16x32_bf16 v[8:11], v[152:155], v[204:207], v[8:11]
	v_mfma_f32_16x16x32_bf16 v[4:7], v[144:147], v[212:215], v[4:7]
	v_mfma_f32_16x16x32_bf16 v[0:3], v[152:155], v[212:215], v[0:3]
	v_mfma_f32_16x16x32_bf16 v[30:33], v[148:151], v[192:195], v[30:33]
	v_mfma_f32_16x16x32_bf16 v[26:29], v[156:159], v[192:195], v[26:29]
	v_mfma_f32_16x16x32_bf16 v[22:25], v[148:151], v[200:203], v[22:25]
	v_mfma_f32_16x16x32_bf16 v[18:21], v[156:159], v[200:203], v[18:21]
	v_mfma_f32_16x16x32_bf16 v[12:15], v[148:151], v[208:211], v[12:15]
	v_mfma_f32_16x16x32_bf16 v[8:11], v[156:159], v[208:211], v[8:11]
	v_mfma_f32_16x16x32_bf16 v[4:7], v[148:151], v[230:233], v[4:7]
	v_mfma_f32_16x16x32_bf16 v[0:3], v[156:159], v[230:233], v[0:3]
	v_mfma_f32_16x16x32_bf16 v[94:97], v[160:163], v[188:191], v[94:97]
	v_mfma_f32_16x16x32_bf16 v[90:93], v[180:183], v[188:191], v[90:93]
	v_mfma_f32_16x16x32_bf16 v[86:89], v[160:163], v[196:199], v[86:89]
	v_mfma_f32_16x16x32_bf16 v[82:85], v[180:183], v[196:199], v[82:85]
	v_mfma_f32_16x16x32_bf16 v[78:81], v[160:163], v[204:207], v[78:81]
	v_mfma_f32_16x16x32_bf16 v[74:77], v[180:183], v[204:207], v[74:77]
	v_mfma_f32_16x16x32_bf16 v[70:73], v[160:163], v[212:215], v[70:73]
	v_mfma_f32_16x16x32_bf16 v[50:53], v[180:183], v[212:215], v[50:53]
	v_mfma_f32_16x16x32_bf16 v[94:97], v[176:179], v[192:195], v[94:97]
	v_mfma_f32_16x16x32_bf16 v[90:93], v[184:187], v[192:195], v[90:93]
	v_mfma_f32_16x16x32_bf16 v[86:89], v[176:179], v[200:203], v[86:89]
	v_mfma_f32_16x16x32_bf16 v[82:85], v[184:187], v[200:203], v[82:85]
	v_mfma_f32_16x16x32_bf16 v[78:81], v[176:179], v[208:211], v[78:81]
	v_mfma_f32_16x16x32_bf16 v[74:77], v[184:187], v[208:211], v[74:77]
	v_mfma_f32_16x16x32_bf16 v[70:73], v[176:179], v[230:233], v[70:73]
	v_mfma_f32_16x16x32_bf16 v[50:53], v[184:187], v[230:233], v[50:53]
	s_barrier
	s_add_u32 s100, s28, 0x80000
	s_addc_u32 s101, s29, 0
	s_mov_b32 m0, s41
	ds_read_b128 v[144:147], v170
	global_load_lds_dwordx4 v130, s[100:101]
	s_mov_b32 m0, s42
	ds_read_b128 v[148:151], v170 offset:1024
	global_load_lds_dwordx4 v134, s[100:101]
	ds_read_b128 v[152:155], v170 offset:2048
	ds_read_b128 v[156:159], v170 offset:3072
	ds_read_b128 v[160:163], v171
	ds_read_b128 v[176:179], v171 offset:1024
	ds_read_b128 v[180:183], v171 offset:2048
	ds_read_b128 v[184:187], v171 offset:3072
	ds_read_b128 v[188:191], v167 offset:32768
	ds_read_b128 v[192:195], v167 offset:33792
	ds_read_b128 v[196:199], v167 offset:34816
	ds_read_b128 v[200:203], v167 offset:35840
	ds_read_b128 v[204:207], v167 offset:36864
	ds_read_b128 v[208:211], v167 offset:37888
	ds_read_b128 v[212:215], v167 offset:38912
	ds_read_b128 v[230:233], v167 offset:39936
	s_waitcnt vmcnt(8) lgkmcnt(0)
	s_barrier
	v_mfma_f32_16x16x32_bf16 v[66:69], v[144:147], v[188:191], v[66:69]
	v_mfma_f32_16x16x32_bf16 v[62:65], v[152:155], v[188:191], v[62:65]
	v_mfma_f32_16x16x32_bf16 v[58:61], v[144:147], v[196:199], v[58:61]
	v_mfma_f32_16x16x32_bf16 v[54:57], v[152:155], v[196:199], v[54:57]
	v_mfma_f32_16x16x32_bf16 v[46:49], v[144:147], v[204:207], v[46:49]
	v_mfma_f32_16x16x32_bf16 v[42:45], v[152:155], v[204:207], v[42:45]
	v_mfma_f32_16x16x32_bf16 v[38:41], v[144:147], v[212:215], v[38:41]
	v_mfma_f32_16x16x32_bf16 v[34:37], v[152:155], v[212:215], v[34:37]
	v_mfma_f32_16x16x32_bf16 v[66:69], v[148:151], v[192:195], v[66:69]
	v_mfma_f32_16x16x32_bf16 v[62:65], v[156:159], v[192:195], v[62:65]
	v_mfma_f32_16x16x32_bf16 v[58:61], v[148:151], v[200:203], v[58:61]
	v_mfma_f32_16x16x32_bf16 v[54:57], v[156:159], v[200:203], v[54:57]
	v_mfma_f32_16x16x32_bf16 v[46:49], v[148:151], v[208:211], v[46:49]
	v_mfma_f32_16x16x32_bf16 v[42:45], v[156:159], v[208:211], v[42:45]
	v_mfma_f32_16x16x32_bf16 v[38:41], v[148:151], v[230:233], v[38:41]
	v_mfma_f32_16x16x32_bf16 v[34:37], v[156:159], v[230:233], v[34:37]
	v_mfma_f32_16x16x32_bf16 v[126:129], v[160:163], v[188:191], v[126:129]
	v_mfma_f32_16x16x32_bf16 v[122:125], v[180:183], v[188:191], v[122:125]
	v_mfma_f32_16x16x32_bf16 v[118:121], v[160:163], v[196:199], v[118:121]
	v_mfma_f32_16x16x32_bf16 v[114:117], v[180:183], v[196:199], v[114:117]
	v_mfma_f32_16x16x32_bf16 v[110:113], v[160:163], v[204:207], v[110:113]
	v_mfma_f32_16x16x32_bf16 v[106:109], v[180:183], v[204:207], v[106:109]
	v_mfma_f32_16x16x32_bf16 v[102:105], v[160:163], v[212:215], v[102:105]
	v_mfma_f32_16x16x32_bf16 v[98:101], v[180:183], v[212:215], v[98:101]
	v_mfma_f32_16x16x32_bf16 v[126:129], v[176:179], v[192:195], v[126:129]
	v_mfma_f32_16x16x32_bf16 v[122:125], v[184:187], v[192:195], v[122:125]
	v_mfma_f32_16x16x32_bf16 v[118:121], v[176:179], v[200:203], v[118:121]
	v_mfma_f32_16x16x32_bf16 v[114:117], v[184:187], v[200:203], v[114:117]
	v_mfma_f32_16x16x32_bf16 v[110:113], v[176:179], v[208:211], v[110:113]
	v_mfma_f32_16x16x32_bf16 v[106:109], v[184:187], v[208:211], v[106:109]
	v_mfma_f32_16x16x32_bf16 v[102:105], v[176:179], v[230:233], v[102:105]
	v_mfma_f32_16x16x32_bf16 v[98:101], v[184:187], v[230:233], v[98:101]
	s_barrier
	s_add_i32 m0, s38, 0x17f80
	ds_read_b128 v[188:191], v167 offset:49152
	global_load_lds_dwordx4 v132, s[26:27] offset:128
	s_add_i32 m0, s38, 0x19f80
	ds_read_b128 v[192:195], v167 offset:50176
	global_load_lds_dwordx4 v136, s[26:27] offset:128
	s_add_i32 m0, s38, 0x1bf80
	ds_read_b128 v[196:199], v167 offset:51200
	global_load_lds_dwordx4 v132, s[64:65] offset:128
	s_add_i32 m0, s38, 0x1df80
	ds_read_b128 v[200:203], v167 offset:52224
	global_load_lds_dwordx4 v136, s[64:65] offset:128
	s_add_i32 m0, s46, 0xffffff80
	ds_read_b128 v[204:207], v167 offset:53248
	global_load_lds_dwordx4 v130, s[28:29] offset:128
	s_add_i32 m0, s47, 0xffffff80
	ds_read_b128 v[208:211], v167 offset:54272
	global_load_lds_dwordx4 v134, s[28:29] offset:128
	ds_read_b128 v[212:215], v167 offset:55296
	ds_read_b128 v[230:233], v167 offset:56320
	s_waitcnt vmcnt(8) lgkmcnt(0)
	s_barrier
	v_mfma_f32_16x16x32_bf16 v[30:33], v[144:147], v[188:191], v[30:33]
	v_mfma_f32_16x16x32_bf16 v[26:29], v[152:155], v[188:191], v[26:29]
	v_mfma_f32_16x16x32_bf16 v[22:25], v[144:147], v[196:199], v[22:25]
	v_mfma_f32_16x16x32_bf16 v[18:21], v[152:155], v[196:199], v[18:21]
	v_mfma_f32_16x16x32_bf16 v[12:15], v[144:147], v[204:207], v[12:15]
	v_mfma_f32_16x16x32_bf16 v[8:11], v[152:155], v[204:207], v[8:11]
	v_mfma_f32_16x16x32_bf16 v[4:7], v[144:147], v[212:215], v[4:7]
	v_mfma_f32_16x16x32_bf16 v[0:3], v[152:155], v[212:215], v[0:3]
	v_mfma_f32_16x16x32_bf16 v[30:33], v[148:151], v[192:195], v[30:33]
	v_mfma_f32_16x16x32_bf16 v[26:29], v[156:159], v[192:195], v[26:29]
	v_mfma_f32_16x16x32_bf16 v[22:25], v[148:151], v[200:203], v[22:25]
	v_mfma_f32_16x16x32_bf16 v[18:21], v[156:159], v[200:203], v[18:21]
	v_mfma_f32_16x16x32_bf16 v[12:15], v[148:151], v[208:211], v[12:15]
	v_mfma_f32_16x16x32_bf16 v[8:11], v[156:159], v[208:211], v[8:11]
	v_mfma_f32_16x16x32_bf16 v[4:7], v[148:151], v[230:233], v[4:7]
	v_mfma_f32_16x16x32_bf16 v[0:3], v[156:159], v[230:233], v[0:3]
	v_mfma_f32_16x16x32_bf16 v[94:97], v[160:163], v[188:191], v[94:97]
	v_mfma_f32_16x16x32_bf16 v[90:93], v[180:183], v[188:191], v[90:93]
	v_mfma_f32_16x16x32_bf16 v[86:89], v[160:163], v[196:199], v[86:89]
	v_mfma_f32_16x16x32_bf16 v[82:85], v[180:183], v[196:199], v[82:85]
	v_mfma_f32_16x16x32_bf16 v[78:81], v[160:163], v[204:207], v[78:81]
	v_mfma_f32_16x16x32_bf16 v[74:77], v[180:183], v[204:207], v[74:77]
	v_mfma_f32_16x16x32_bf16 v[70:73], v[160:163], v[212:215], v[70:73]
	v_mfma_f32_16x16x32_bf16 v[50:53], v[180:183], v[212:215], v[50:53]
	v_mfma_f32_16x16x32_bf16 v[94:97], v[176:179], v[192:195], v[94:97]
	v_mfma_f32_16x16x32_bf16 v[90:93], v[184:187], v[192:195], v[90:93]
	v_mfma_f32_16x16x32_bf16 v[86:89], v[176:179], v[200:203], v[86:89]
	v_mfma_f32_16x16x32_bf16 v[82:85], v[184:187], v[200:203], v[82:85]
	v_mfma_f32_16x16x32_bf16 v[78:81], v[176:179], v[208:211], v[78:81]
	v_mfma_f32_16x16x32_bf16 v[74:77], v[184:187], v[208:211], v[74:77]
	v_mfma_f32_16x16x32_bf16 v[70:73], v[176:179], v[230:233], v[70:73]
	v_mfma_f32_16x16x32_bf16 v[50:53], v[184:187], v[230:233], v[50:53]
	s_barrier
	s_add_i32 s62, s62, 2
	s_add_u32 s24, s24, 0x100
	s_addc_u32 s25, s25, 0
	s_add_u32 s60, s60, 0x100
	s_addc_u32 s61, s61, 0
	s_cmp_gt_u32 s62, 29
	s_cbranch_scc0 .LBB0_1018
	s_and_b64 vcc, exec, s[8:9]
	s_cbranch_vccz .LBB0_1021
	s_barrier
